# v017 with the whole code image shifted by 128 bytes (entry padding), placement only
# baseline (speedup 1.0000x reference)
; #define LAS __attribute__((address_space(3)))
; __global__ __launch_bounds__(512, 2) void fwd_megakernel(Params P) {
;     extern __shared__ __attribute__((aligned(16))) char shm[];
;     cg::grid_group grid = cg::this_grid();
;     volatile LAS unsigned* st = (volatile LAS unsigned*)(shm + STAGE_BYTES);
;     if (threadIdx.x == 0) { st[0] = 0u; st[1] = 0u; }
_Z14fwd_megakernel6Params:
	s_load_dwordx2 s[72:73], s[0:1], 0xd0
	s_load_dword s85, s[0:1], 0xd8
	s_mov_b64 s[82:83], s[0:1]
	s_nop 0
	s_nop 0
	s_nop 0
	s_nop 0
	s_nop 0
	s_nop 0
	s_nop 0
	s_nop 0
	s_nop 0
	s_nop 0
	s_nop 0
	s_nop 0
	s_nop 0
	s_nop 0
	s_nop 0
	s_nop 0
	s_nop 0
	s_nop 0
	s_nop 0
	s_nop 0
	s_nop 0
	s_nop 0
	s_nop 0
	s_nop 0
	s_nop 0
	s_nop 0
	s_nop 0
	s_nop 0
	s_nop 0
	s_nop 0
	s_nop 0
	s_nop 0
	s_add_u32 s6, s82, 0xd0
	v_and_b32_e32 v254, 0x3ff, v0
	s_mov_b32 s90, s2
	s_addc_u32 s7, s83, 0
	v_cmp_eq_u32_e64 s[88:89], 0, v254
	s_and_saveexec_b64 s[4:5], s[88:89]
	s_cbranch_execz .LBB0_2
	s_add_i32 s0, 0, 0x20000
	v_mov_b32_e32 v1, 0
	v_mov_b32_e32 v2, s0
	s_add_i32 s0, 0, 0x20004
	ds_write_b32 v2, v1
	v_mov_b32_e32 v2, s0
	ds_write_b32 v2, v1
